# attention units (dif, swa): one static s_setprio 1 for the younger wave half (waves 4-7) at unit start
# speedup vs baseline: 1.0028x; 1.0028x over previous
; #define LAS __attribute__((address_space(3)))
; __device__ __forceinline__ void attn_dif_unit(LAS unsigned char* lds, const int tid, const int wave_s, const bf16_t* q, const bf16_t* k0, const bf16_t* k1, const bf16_t* vt0, const bf16_t* vt1, ...
;     const int lane = tid & 63, w = tid >> 6, c32 = lane & 31, hi = lane >> 5, srow = tid >> 3, sch = tid & 7;
;     LAS unsigned char* qb = lds + DA_Q + w * DA_QW;
; #pragma unroll
;     for (int i = 0; i < 8; ++i) { int lq = lane, wq = w; asm volatile("" : "+v"(lq), "+v"(wq)); const int e = lq + 64 * i, r = e >> 4, c = e & 15;
;         *(LAS u32x4*)(qb + r * DA_KP + c * 16) = *(const u32x4*)((const char*)q + (unsigned)(((32 * wq + r) * D + c * 8) * 2)); }
;     f32x16 oacc[2][4];
; #pragma unroll
;     for (int m = 0; m < 2; ++m)
; #pragma unroll
;         for (int i = 0; i < 4; ++i)
; #pragma unroll
;             for (int r = 0; r < 16; ++r) oacc[m][i][r] = 0.f;
;     float m_used[2] = {0.f, 0.f}, l_run[2] = {0.f, 0.f};
;     const int ntile = nt0 + nt1;
;     u32x4 kreg[2], vreg[2];
;     const unsigned koff = (unsigned)(srow * D + sch * 8) * 2u, voff = (unsigned)(srow * NTOK + sch * 8) * 2u;
;     ...
;     DA_LOAD(0);
; #pragma unroll 1
;     for (int t = 0; t < ntile; ++t) {
;         LAS unsigned char* kb = lds + (t & 1) * DA_BUF; LAS unsigned char* vb = kb + DA_KT;
; #pragma unroll
;         for (int i = 0; i < 2; ++i) { *(LAS u32x4*)(kb + srow * DA_KP + (sch + 8 * i) * 16) = kreg[i];
;             LAS unsigned char* p = vb + (srow + 64 * i) * DA_VP + (sch >> 1) * 32 + (sch & 1) * 8; *(LAS u32x2*)p = (u32x2){vreg[i].x, vreg[i].y}; *(LAS u32x2*)(p + 16) = (u32x2){vreg[i].z, vreg[i].w}; }
;         asm volatile("s_waitcnt lgkmcnt(0)" ::: "memory"); __builtin_amdgcn_s_barrier(); asm volatile("" ::: "memory");
;         if (wave_s >= 4) __builtin_amdgcn_s_sleep(DA_SKEW);
; #pragma unroll
.LBB0_425:
	s_cmp_lg_u64 s[80:81], 0
	s_cbranch_scc0 .Lprio_skip1
	s_setprio 1
